# same as previous version with code placement shifted by 16 bytes (4 s_nop at entry)
# baseline (speedup 1.0000x reference)
; #define LAS __attribute__((address_space(3)))
; __device__ __forceinline__ unsigned xb_add(unsigned* p, unsigned v) { return __hip_atomic_fetch_add(p, v, __ATOMIC_RELAXED, __HIP_MEMORY_SCOPE_AGENT); }
; __device__ __forceinline__ unsigned xb_xcc_id() { return (unsigned)__builtin_amdgcn_s_getreg((3 << 11) | 20) & 0xFu; }
; __global__ void __launch_bounds__(NTHREADS, 2) fwd_mega(P prm) {
;     extern __shared__ __attribute__((aligned(16))) unsigned char lds_raw[];
;     LAS unsigned char* lds = (LAS unsigned char*)lds_raw;
;     cg::grid_group grid = cg::this_grid();
;     const int G = gridDim.x, NGW = G * 8, NGT = G * NTHREADS;
;     const int wave_s = __builtin_amdgcn_readfirstlane(threadIdx.x >> 6);
;     if (threadIdx.x < 64) ((LAS unsigned*)(lds + LDS_ST))[threadIdx.x] = 0u;
;     __syncthreads();
;     if (threadIdx.x == 0) (void)xb_add((unsigned*)(prm.ws + WS_BAR) + XB_XCNT(xb_xcc_id()), 1u);
_Z8fwd_mega1P:
	s_nop 0
	s_nop 0
	s_nop 0
	s_nop 0
	s_mov_b64 s[84:85], s[0:1]
	s_add_u32 s90, s84, 0xd8
	v_and_b32_e32 v97, 0x3ff, v0
	s_mov_b32 s88, s2
	s_addc_u32 s91, s85, 0
	v_readfirstlane_b32 s86, v97
	v_cmp_gt_u32_e32 vcc, 64, v97
	s_and_saveexec_b64 s[0:1], vcc
	v_lshl_add_u32 v1, v97, 2, 0
	v_add_u32_e32 v1, 0x20000, v1
	v_mov_b32_e32 v2, 0
	ds_write_b32 v1, v2
	s_or_b64 exec, exec, s[0:1]
	s_load_dwordx2 s[0:1], s[84:85], 0xd8
	s_load_dword s83, s[84:85], 0xe0
	v_cmp_eq_u32_e32 vcc, 0, v97
	s_waitcnt lgkmcnt(0)
	s_barrier
	v_writelane_b32 v254, s0, 0
	s_nop 1
	v_writelane_b32 v254, s1, 1
	s_and_saveexec_b64 s[0:1], vcc
	s_cbranch_execz .LBB0_5
	s_mov_b64 s[2:3], exec
	v_mbcnt_lo_u32_b32 v1, s2, 0
	v_mbcnt_hi_u32_b32 v1, s3, v1
	v_cmp_eq_u32_e32 vcc, 0, v1
	s_getreg_b32 s4, hwreg(HW_REG_XCC_ID, 0, 4)
	s_and_b64 s[6:7], exec, vcc
	s_mov_b64 exec, s[6:7]
	s_cbranch_execz .LBB0_5
	s_load_dwordx2 s[6:7], s[84:85], 0xd0
	s_lshl_b32 s4, s4, 8
	s_and_b32 s4, s4, 0xf00
	v_mov_b32_e32 v1, 0x80000
	s_waitcnt lgkmcnt(0)
	s_add_u32 s4, s6, s4
	s_addc_u32 s5, s7, 0
	s_bcnt1_i32_b64 s2, s[2:3]
	v_mov_b32_e32 v2, s2
	global_atomic_add v1, v2, s[4:5] offset:1024
